# FoX diagonal tiles: causal mask by wave-uniform half classification + 16 precomputed lane masks instead of a v_or / v_cmp / v_cndmask triple per score
# speedup vs baseline: 1.0086x; 1.0045x over previous
.LBB0_786:
	v_lshl_add_u64 v[168:169], s[0:1], 0, v[0:1]
	v_cmp_gt_u32_e32 vcc, 32, v21
	v_mov_b32_e32 v0, 0x3f80
	s_mov_b32 s0, 0x5040100
	v_cndmask_b32_e32 v0, 0, v0, vcc
	v_mov_b32_e32 v14, v1
	v_mov_b32_e32 v15, v1
	s_waitcnt lgkmcnt(0)
	s_barrier
	v_mul_u32_u24_e32 v173, 0x90, v20
	v_perm_b32 v148, v0, v0, s0
	v_mov_b32_e32 v0, v1
	v_mov_b32_e32 v2, v1
	v_mov_b32_e32 v3, v1
	v_mov_b32_e32 v4, v1
	v_mov_b32_e32 v5, v1
	v_mov_b32_e32 v6, v1
	v_mov_b32_e32 v7, v1
	v_mov_b32_e32 v8, v1
	v_mov_b32_e32 v9, v1
	v_mov_b32_e32 v10, v1
	v_mov_b32_e32 v11, v1
	v_mov_b32_e32 v12, v1
	v_mov_b32_e32 v13, v1
	v_mov_b64_e32 v[50:51], v[14:15]
	v_mov_b64_e32 v[34:35], v[14:15]
	s_pack_ll_b32_b16 s0, 0, 0
	v_mov_b64_e32 v[48:49], v[12:13]
	v_mov_b64_e32 v[46:47], v[10:11]
	v_mov_b64_e32 v[44:45], v[8:9]
	v_mov_b64_e32 v[42:43], v[6:7]
	v_mov_b64_e32 v[40:41], v[4:5]
	v_mov_b64_e32 v[38:39], v[2:3]
	v_mov_b64_e32 v[36:37], v[0:1]
	v_mov_b64_e32 v[32:33], v[12:13]
	v_mov_b64_e32 v[30:31], v[10:11]
	v_mov_b64_e32 v[28:29], v[8:9]
	v_mov_b64_e32 v[26:27], v[6:7]
	v_mov_b64_e32 v[24:25], v[4:5]
	v_mov_b64_e32 v[22:23], v[2:3]
	v_mov_b64_e32 v[20:21], v[0:1]
	v_mov_b64_e32 v[18:19], v[14:15]
	s_mov_b32 s13, 4
	v_mov_b32_e32 v149, s0
	v_mov_b32_e32 v150, s0
	v_mov_b32_e32 v151, s0
	v_lshlrev_b32_e32 v158, 2, v153
	v_add3_u32 v174, s33, v173, v156
	s_mov_b32 s17, 0
	v_mov_b32_e32 v86, 0
	s_mov_b32 s19, s92
	v_mov_b64_e32 v[16:17], v[12:13]
	v_mov_b64_e32 v[14:15], v[10:11]
	v_mov_b64_e32 v[12:13], v[8:9]
	v_mov_b64_e32 v[10:11], v[6:7]
	v_mov_b64_e32 v[8:9], v[4:5]
	v_mov_b64_e32 v[6:7], v[2:3]
	v_mov_b64_e32 v[4:5], v[0:1]
	v_and_b32_e32 v52, 31, v186
	v_or_b32_e32 v53, 0, v158
	v_cmp_le_u32_e64 s[36:37], v53, v52
	v_or_b32_e32 v53, 1, v158
	v_cmp_le_u32_e64 s[38:39], v53, v52
	v_or_b32_e32 v53, 2, v158
	v_cmp_le_u32_e64 s[40:41], v53, v52
	v_or_b32_e32 v53, 3, v158
	v_cmp_le_u32_e64 s[42:43], v53, v52
	v_or_b32_e32 v53, 8, v158
	v_cmp_le_u32_e64 s[44:45], v53, v52
	v_or_b32_e32 v53, 9, v158
	v_cmp_le_u32_e64 s[46:47], v53, v52
	v_or_b32_e32 v53, 10, v158
	v_cmp_le_u32_e64 s[48:49], v53, v52
	v_or_b32_e32 v53, 11, v158
	v_cmp_le_u32_e64 s[50:51], v53, v52
	v_or_b32_e32 v53, 16, v158
	v_cmp_le_u32_e64 s[52:53], v53, v52
	v_or_b32_e32 v53, 17, v158
	v_cmp_le_u32_e64 s[54:55], v53, v52
	v_or_b32_e32 v53, 18, v158
	v_cmp_le_u32_e64 s[56:57], v53, v52
	v_or_b32_e32 v53, 19, v158
	v_cmp_le_u32_e64 s[58:59], v53, v52
	v_or_b32_e32 v53, 24, v158
	v_cmp_le_u32_e64 s[60:61], v53, v52
	v_or_b32_e32 v53, 25, v158
	v_cmp_le_u32_e64 s[62:63], v53, v52
	v_or_b32_e32 v53, 26, v158
	v_cmp_le_u32_e64 s[70:71], v53, v52
	v_or_b32_e32 v53, 27, v158
	v_cmp_le_u32_e64 s[72:73], v53, v52
	s_branch .LBB0_790

.LBB0_794:
	s_mul_i32 s8, s17, 0x4900
	s_add_i32 s20, s33, s8
	v_add_u32_e32 v0, s20, v173
	v_add_u32_e32 v0, v0, v156
	ds_read_b128 v[52:55], v0
	ds_read_b128 v[88:91], v0 offset:32
	ds_read_b128 v[92:95], v0 offset:4608
	ds_read_b128 v[96:99], v0 offset:4640
	ds_read_b128 v[100:103], v0 offset:64
	ds_read_b128 v[104:107], v0 offset:96
	ds_read_b128 v[108:111], v0 offset:4672
	ds_read_b128 v[112:115], v0 offset:4704
	s_waitcnt lgkmcnt(7)
	v_mfma_f32_32x32x16_bf16 v[68:83], v[52:55], v[116:119], v[4:19]
	s_waitcnt lgkmcnt(5)
	v_mfma_f32_32x32x16_bf16 v[52:67], v[92:95], v[116:119], v[4:19]
	v_mfma_f32_32x32x16_bf16 v[68:83], v[88:91], v[120:123], v[68:83]
	ds_read_b128 v[88:91], v0 offset:128
	ds_read_b128 v[92:95], v0 offset:4736
	s_waitcnt lgkmcnt(6)
	v_mfma_f32_32x32x16_bf16 v[52:67], v[96:99], v[120:123], v[52:67]
	s_waitcnt lgkmcnt(5)
	v_mfma_f32_32x32x16_bf16 v[68:83], v[100:103], v[124:127], v[68:83]
	s_waitcnt lgkmcnt(3)
	v_mfma_f32_32x32x16_bf16 v[52:67], v[108:111], v[124:127], v[52:67]
	v_mfma_f32_32x32x16_bf16 v[68:83], v[104:107], v[128:131], v[68:83]
	s_waitcnt lgkmcnt(2)
	v_mfma_f32_32x32x16_bf16 v[52:67], v[112:115], v[128:131], v[52:67]
	s_waitcnt lgkmcnt(1)
	v_mfma_f32_32x32x16_bf16 v[68:83], v[88:91], v[148:151], v[68:83]
	s_waitcnt lgkmcnt(0)
	v_mfma_f32_32x32x16_bf16 v[52:67], v[92:95], v[148:151], v[52:67]
	v_mov_b32_e32 v2, s19
	ds_read_b32 v2, v2
	s_waitcnt lgkmcnt(0)
	v_cmp_gt_i32_e32 vcc, s18, v2
	s_cbranch_vccnz .LBB0_796
	v_readfirstlane_b32 s34, v2
	v_readfirstlane_b32 s35, v154
	s_nop 1
	s_lshl_b32 s34, s34, 1
	s_lshr_b32 s35, s35, 5
	s_cmp_lt_u32 s34, s35
	s_cbranch_scc1 .Lfm1_d0
	s_cmp_eq_u32 s34, s35
	s_cbranch_scc1 .Lfm1_t0
	v_mov_b32_e32 v68, v185
	v_mov_b32_e32 v69, v185
	v_mov_b32_e32 v70, v185
	v_mov_b32_e32 v71, v185
	v_mov_b32_e32 v72, v185
	v_mov_b32_e32 v73, v185
	v_mov_b32_e32 v74, v185
	v_mov_b32_e32 v75, v185
	v_mov_b32_e32 v76, v185
	v_mov_b32_e32 v77, v185
	v_mov_b32_e32 v78, v185
	v_mov_b32_e32 v79, v185
	v_mov_b32_e32 v80, v185
	v_mov_b32_e32 v81, v185
	v_mov_b32_e32 v82, v185
	v_mov_b32_e32 v83, v185
	s_branch .Lfm1_d0
.Lfm1_t0:
	v_cndmask_b32_e64 v68, v185, v68, s[36:37]
	v_cndmask_b32_e64 v69, v185, v69, s[38:39]
	v_cndmask_b32_e64 v70, v185, v70, s[40:41]
	v_cndmask_b32_e64 v71, v185, v71, s[42:43]
	v_cndmask_b32_e64 v72, v185, v72, s[44:45]
	v_cndmask_b32_e64 v73, v185, v73, s[46:47]
	v_cndmask_b32_e64 v74, v185, v74, s[48:49]
	v_cndmask_b32_e64 v75, v185, v75, s[50:51]
	v_cndmask_b32_e64 v76, v185, v76, s[52:53]
	v_cndmask_b32_e64 v77, v185, v77, s[54:55]
	v_cndmask_b32_e64 v78, v185, v78, s[56:57]
	v_cndmask_b32_e64 v79, v185, v79, s[58:59]
	v_cndmask_b32_e64 v80, v185, v80, s[60:61]
	v_cndmask_b32_e64 v81, v185, v81, s[62:63]
	v_cndmask_b32_e64 v82, v185, v82, s[70:71]
	v_cndmask_b32_e64 v83, v185, v83, s[72:73]
.Lfm1_d0:
	s_add_u32 s34, s34, 1
	s_cmp_lt_u32 s34, s35
	s_cbranch_scc1 .Lfm1_d1
	s_cmp_eq_u32 s34, s35
	s_cbranch_scc1 .Lfm1_t1
	v_mov_b32_e32 v52, v185
	v_mov_b32_e32 v53, v185
	v_mov_b32_e32 v54, v185
	v_mov_b32_e32 v55, v185
	v_mov_b32_e32 v56, v185
	v_mov_b32_e32 v57, v185
	v_mov_b32_e32 v58, v185
	v_mov_b32_e32 v59, v185
	v_mov_b32_e32 v60, v185
	v_mov_b32_e32 v61, v185
	v_mov_b32_e32 v62, v185
	v_mov_b32_e32 v63, v185
	v_mov_b32_e32 v64, v185
	v_mov_b32_e32 v65, v185
	v_mov_b32_e32 v66, v185
	v_mov_b32_e32 v67, v185
	s_branch .Lfm1_d1
.Lfm1_t1:
	v_cndmask_b32_e64 v52, v185, v52, s[36:37]
	v_cndmask_b32_e64 v53, v185, v53, s[38:39]
	v_cndmask_b32_e64 v54, v185, v54, s[40:41]
	v_cndmask_b32_e64 v55, v185, v55, s[42:43]
	v_cndmask_b32_e64 v56, v185, v56, s[44:45]
	v_cndmask_b32_e64 v57, v185, v57, s[46:47]
	v_cndmask_b32_e64 v58, v185, v58, s[48:49]
	v_cndmask_b32_e64 v59, v185, v59, s[50:51]
	v_cndmask_b32_e64 v60, v185, v60, s[52:53]
	v_cndmask_b32_e64 v61, v185, v61, s[54:55]
	v_cndmask_b32_e64 v62, v185, v62, s[56:57]
	v_cndmask_b32_e64 v63, v185, v63, s[58:59]
	v_cndmask_b32_e64 v64, v185, v64, s[60:61]
	v_cndmask_b32_e64 v65, v185, v65, s[62:63]
	v_cndmask_b32_e64 v66, v185, v66, s[70:71]
	v_cndmask_b32_e64 v67, v185, v67, s[72:73]
.Lfm1_d1:
.LBB0_796:
	s_nop 7

.LBB0_807:
	s_mulk_i32 s22, 0x4900
	v_add_u32_e32 v0, s22, v174
	ds_read_b128 v[52:55], v0
	ds_read_b128 v[56:59], v0 offset:32
	ds_read_b128 v[60:63], v0 offset:4608
	ds_read_b128 v[64:67], v0 offset:4640
	ds_read_b128 v[68:71], v0 offset:64
	ds_read_b128 v[72:75], v0 offset:96
	ds_read_b128 v[76:79], v0 offset:4672
	ds_read_b128 v[80:83], v0 offset:4704
	s_waitcnt lgkmcnt(7)
	v_mfma_f32_32x32x16_bf16 v[100:115], v[52:55], v[116:119], v[4:19]
	s_waitcnt lgkmcnt(5)
	v_mfma_f32_32x32x16_bf16 v[84:99], v[60:63], v[116:119], v[4:19]
	v_mfma_f32_32x32x16_bf16 v[100:115], v[56:59], v[120:123], v[100:115]
	ds_read_b128 v[52:55], v0 offset:128
	ds_read_b128 v[56:59], v0 offset:4736
	s_waitcnt lgkmcnt(6)
	v_mfma_f32_32x32x16_bf16 v[84:99], v[64:67], v[120:123], v[84:99]
	s_waitcnt lgkmcnt(5)
	v_mfma_f32_32x32x16_bf16 v[100:115], v[68:71], v[124:127], v[100:115]
	s_waitcnt lgkmcnt(3)
	v_mfma_f32_32x32x16_bf16 v[84:99], v[76:79], v[124:127], v[84:99]
	v_mfma_f32_32x32x16_bf16 v[100:115], v[72:75], v[128:131], v[100:115]
	s_waitcnt lgkmcnt(2)
	v_mfma_f32_32x32x16_bf16 v[84:99], v[80:83], v[128:131], v[84:99]
	s_waitcnt lgkmcnt(1)
	v_mfma_f32_32x32x16_bf16 v[100:115], v[52:55], v[148:151], v[100:115]
	s_waitcnt lgkmcnt(0)
	v_mfma_f32_32x32x16_bf16 v[84:99], v[56:59], v[148:151], v[84:99]
	v_mov_b32_e32 v2, s19
	ds_read_b32 v2, v2 offset:4
	s_waitcnt lgkmcnt(0)
	v_cmp_gt_i32_e32 vcc, s18, v2
	s_cbranch_vccnz .LBB0_809
	v_readfirstlane_b32 s34, v2
	v_readfirstlane_b32 s35, v154
	s_nop 1
	s_lshl_b32 s34, s34, 1
	s_lshr_b32 s35, s35, 5
	s_cmp_lt_u32 s34, s35
	s_cbranch_scc1 .Lfm2_d0
	s_cmp_eq_u32 s34, s35
	s_cbranch_scc1 .Lfm2_t0
	v_mov_b32_e32 v100, v185
	v_mov_b32_e32 v101, v185
	v_mov_b32_e32 v102, v185
	v_mov_b32_e32 v103, v185
	v_mov_b32_e32 v104, v185
	v_mov_b32_e32 v105, v185
	v_mov_b32_e32 v106, v185
	v_mov_b32_e32 v107, v185
	v_mov_b32_e32 v108, v185
	v_mov_b32_e32 v109, v185
	v_mov_b32_e32 v110, v185
	v_mov_b32_e32 v111, v185
	v_mov_b32_e32 v112, v185
	v_mov_b32_e32 v113, v185
	v_mov_b32_e32 v114, v185
	v_mov_b32_e32 v115, v185
	s_branch .Lfm2_d0
.Lfm2_t0:
	v_cndmask_b32_e64 v100, v185, v100, s[36:37]
	v_cndmask_b32_e64 v101, v185, v101, s[38:39]
	v_cndmask_b32_e64 v102, v185, v102, s[40:41]
	v_cndmask_b32_e64 v103, v185, v103, s[42:43]
	v_cndmask_b32_e64 v104, v185, v104, s[44:45]
	v_cndmask_b32_e64 v105, v185, v105, s[46:47]
	v_cndmask_b32_e64 v106, v185, v106, s[48:49]
	v_cndmask_b32_e64 v107, v185, v107, s[50:51]
	v_cndmask_b32_e64 v108, v185, v108, s[52:53]
	v_cndmask_b32_e64 v109, v185, v109, s[54:55]
	v_cndmask_b32_e64 v110, v185, v110, s[56:57]
	v_cndmask_b32_e64 v111, v185, v111, s[58:59]
	v_cndmask_b32_e64 v112, v185, v112, s[60:61]
	v_cndmask_b32_e64 v113, v185, v113, s[62:63]
	v_cndmask_b32_e64 v114, v185, v114, s[70:71]
	v_cndmask_b32_e64 v115, v185, v115, s[72:73]
.Lfm2_d0:
	s_add_u32 s34, s34, 1
	s_cmp_lt_u32 s34, s35
	s_cbranch_scc1 .Lfm2_d1
	s_cmp_eq_u32 s34, s35
	s_cbranch_scc1 .Lfm2_t1
	v_mov_b32_e32 v84, v185
	v_mov_b32_e32 v85, v185
	v_mov_b32_e32 v86, v185
	v_mov_b32_e32 v87, v185
	v_mov_b32_e32 v88, v185
	v_mov_b32_e32 v89, v185
	v_mov_b32_e32 v90, v185
	v_mov_b32_e32 v91, v185
	v_mov_b32_e32 v92, v185
	v_mov_b32_e32 v93, v185
	v_mov_b32_e32 v94, v185
	v_mov_b32_e32 v95, v185
	v_mov_b32_e32 v96, v185
	v_mov_b32_e32 v97, v185
	v_mov_b32_e32 v98, v185
	v_mov_b32_e32 v99, v185
	s_branch .Lfm2_d1
.Lfm2_t1:
	v_cndmask_b32_e64 v84, v185, v84, s[36:37]
	v_cndmask_b32_e64 v85, v185, v85, s[38:39]
	v_cndmask_b32_e64 v86, v185, v86, s[40:41]
	v_cndmask_b32_e64 v87, v185, v87, s[42:43]
	v_cndmask_b32_e64 v88, v185, v88, s[44:45]
	v_cndmask_b32_e64 v89, v185, v89, s[46:47]
	v_cndmask_b32_e64 v90, v185, v90, s[48:49]
	v_cndmask_b32_e64 v91, v185, v91, s[50:51]
	v_cndmask_b32_e64 v92, v185, v92, s[52:53]
	v_cndmask_b32_e64 v93, v185, v93, s[54:55]
	v_cndmask_b32_e64 v94, v185, v94, s[56:57]
	v_cndmask_b32_e64 v95, v185, v95, s[58:59]
	v_cndmask_b32_e64 v96, v185, v96, s[60:61]
	v_cndmask_b32_e64 v97, v185, v97, s[62:63]
	v_cndmask_b32_e64 v98, v185, v98, s[70:71]
	v_cndmask_b32_e64 v99, v185, v99, s[72:73]
